# attention: first-half K/V global loads interleaved with the trailing cvt_pk instructions
# speedup vs baseline: 1.0164x; 1.0164x over previous
; #define SBAR() __builtin_amdgcn_sched_barrier(0)
; __device__ __forceinline__ void finishSM(f32x16& p0, f32x16& p1, float alpha, float& l_reg, bf16x8& pa0, bf16x8& pa1, bf16x8& pa2, bf16x8& pa3) {
;   for (int r = 0; r < 16; ++r) p1[r] = __builtin_amdgcn_exp2f(p1[r]);
;   float ps = 0; for (int r = 0; r < 16; ++r) ps += p0[r]; for (int r = 0; r < 16; ++r) ps += p1[r];
;   { auto rr = __builtin_amdgcn_permlane32_swap(__float_as_uint(ps), __float_as_uint(ps), false, false);
;     ps = __uint_as_float(rr[0]) + __uint_as_float(rr[1]); }
;   l_reg = l_reg * alpha + ps;
;     ...
;   PK4(p0, 0, pa0); PK4(p0, 8, pa1); PK4(p1, 0, pa2); PK4(p1, 8, pa3);
; template <typename TQ>
; __device__ __forceinline__ void attn_dense_body(const TQ* __restrict__ Qb, const bf16* __restrict__ Kh, const bf16* __restrict__ Vh,
;                                                 unsigned short* __restrict__ Ob, int seq, char* lds, const int wave_s) {
;     ...
;     SBAR(); qkt(pB0, pB1, (bf16*)((char*)K_lds + SHM_K), qr, r32, hi);
;     finishSM(pA0, pA1, alA, l_reg, pa0, pa1, pa2, pa3); SBAR();
.LBB0_575:
	ds_read_b128 v[64:67], v189 offset:49152
	ds_read_b128 v[68:71], v189 offset:57344
	ds_read_b128 v[210:213], v199 offset:49152
	ds_read_b128 v[214:217], v199 offset:57344
	ds_read_b128 v[240:243], v192 offset:49152
	ds_read_b128 v[244:247], v192 offset:57344
	v_add_f32_e32 v160, v175, v161
	s_waitcnt lgkmcnt(5)
	v_mfma_f32_32x32x16_bf16 v[80:95], v[64:67], v[112:115], 0
	v_add_f32_e32 v160, v162, v160
	v_add_f32_e32 v160, v206, v160
	v_add_f32_e32 v160, v174, v160
	v_add_f32_e32 v160, v209, v160
	v_add_f32_e32 v160, v163, v160
	v_add_f32_e32 v160, v173, v160
	v_add_f32_e32 v160, v169, v160
	s_waitcnt lgkmcnt(4)
	v_mfma_f32_32x32x16_bf16 v[64:79], v[68:71], v[112:115], 0
	v_add_f32_e32 v160, v171, v160
	v_add_f32_e32 v160, v170, v160
	v_add_f32_e32 v160, v172, v160
	v_exp_f32_e32 v158, v158
	v_add_f32_e32 v160, v165, v160
	v_exp_f32_e32 v159, v159
	v_add_f32_e32 v160, v167, v160
	s_waitcnt lgkmcnt(3)
	v_mfma_f32_32x32x16_bf16 v[80:95], v[210:213], v[108:111], v[80:95]
	v_exp_f32_e32 v156, v156
	v_add_f32_e32 v160, v166, v160
	v_exp_f32_e32 v157, v157
	v_add_f32_e32 v160, v168, v160
	v_exp_f32_e32 v152, v152
	v_add_f32_e32 v160, v158, v160
	v_exp_f32_e32 v153, v153
	s_waitcnt lgkmcnt(2)
	v_mfma_f32_32x32x16_bf16 v[64:79], v[214:217], v[108:111], v[64:79]
	ds_read_b128 v[210:213], v191 offset:49152
	ds_read_b128 v[214:217], v191 offset:57344
	v_add_f32_e32 v160, v159, v160
	v_exp_f32_e32 v148, v148
	v_add_f32_e32 v160, v156, v160
	v_exp_f32_e32 v149, v149
	v_add_f32_e32 v160, v157, v160
	v_exp_f32_e32 v146, v146
	s_waitcnt lgkmcnt(3)
	v_mfma_f32_32x32x16_bf16 v[80:95], v[240:243], v[120:123], v[80:95]
	v_add_f32_e32 v160, v152, v160
	v_exp_f32_e32 v147, v147
	v_add_f32_e32 v160, v153, v160
	v_exp_f32_e32 v154, v154
	v_add_f32_e32 v160, v148, v160
	v_exp_f32_e32 v155, v155
	v_add_f32_e32 v160, v149, v160
	s_waitcnt lgkmcnt(2)
	v_mfma_f32_32x32x16_bf16 v[64:79], v[244:247], v[120:123], v[64:79]
	ds_read_b128 v[240:243], v189 offset:49280
	ds_read_b128 v[244:247], v189 offset:57472
	v_exp_f32_e32 v150, v150
	v_add_f32_e32 v160, v146, v160
	v_exp_f32_e32 v151, v151
	v_add_f32_e32 v160, v147, v160
	v_exp_f32_e32 v144, v144
	v_add_f32_e32 v160, v154, v160
	s_waitcnt lgkmcnt(3)
	v_mfma_f32_32x32x16_bf16 v[80:95], v[210:213], v[124:127], v[80:95]
	v_exp_f32_e32 v145, v145
	v_add_f32_e32 v160, v155, v160
	v_add_f32_e32 v160, v150, v160
	v_add_f32_e32 v160, v151, v160
	v_add_f32_e32 v160, v144, v160
	v_add_f32_e32 v203, v145, v160
	s_waitcnt lgkmcnt(2)
	v_mfma_f32_32x32x16_bf16 v[64:79], v[214:217], v[124:127], v[64:79]
	ds_read_b128 v[210:213], v199 offset:49280
	ds_read_b128 v[214:217], v199 offset:57472
	s_waitcnt lgkmcnt(3)
	v_mfma_f32_32x32x16_bf16 v[80:95], v[240:243], v[116:119], v[80:95]
	s_waitcnt lgkmcnt(2)
	v_mfma_f32_32x32x16_bf16 v[64:79], v[244:247], v[116:119], v[64:79]
	ds_read_b128 v[240:243], v192 offset:49280
	ds_read_b128 v[244:247], v192 offset:57472
	s_waitcnt lgkmcnt(3)
	v_mfma_f32_32x32x16_bf16 v[80:95], v[210:213], v[104:107], v[80:95]
	s_waitcnt lgkmcnt(2)
	v_mfma_f32_32x32x16_bf16 v[64:79], v[214:217], v[104:107], v[64:79]
	ds_read_b128 v[210:213], v191 offset:49280
	ds_read_b128 v[214:217], v191 offset:57472
	s_waitcnt lgkmcnt(3)
	v_mfma_f32_32x32x16_bf16 v[80:95], v[240:243], v[100:103], v[80:95]
	s_waitcnt lgkmcnt(2)
	v_mfma_f32_32x32x16_bf16 v[64:79], v[244:247], v[100:103], v[64:79]
	v_cvt_pk_bf16_f32 v160, v161, v175
	v_cvt_pk_bf16_f32 v161, v162, v206
	v_cvt_pk_bf16_f32 v162, v174, v209
	v_cvt_pk_bf16_f32 v163, v163, v173
	v_cvt_pk_bf16_f32 v206, v169, v171
	v_cvt_pk_bf16_f32 v207, v170, v172
	s_waitcnt lgkmcnt(1)
	v_mfma_f32_32x32x16_bf16 v[80:95], v[210:213], v[96:99], v[80:95]
	v_cvt_pk_bf16_f32 v208, v165, v167
	v_cvt_pk_bf16_f32 v209, v166, v168
	v_cvt_pk_bf16_f32 v166, v158, v159
	v_cvt_pk_bf16_f32 v167, v156, v157
	v_cvt_pk_bf16_f32 v168, v152, v153
	s_waitcnt lgkmcnt(0)
; #define SBAR() __builtin_amdgcn_sched_barrier(0)
; #define SLOAD(i, k0) do { sr_[i].vs0 = St::ld8(&Vh[(long)((k0) + sr) * LDK + sc]); sr_[i].vs1 = St::ld8(&Vh[(long)((k0) + 32 + sr) * LDK + sc]); \
;     sr_[i].ks0 = St::ld8(&Kh[(long)((k0) + sr) * LDK + sc]); sr_[i].ks1 = St::ld8(&Kh[(long)((k0) + 32 + sr) * LDK + sc]); } while (0)
; template <int D0> __device__ __forceinline__ void pv_one(f32x16& od, int vb, bf16x8 pa0, bf16x8 pa1, bf16x8 pa2, bf16x8 pa3) {
;   const s16x4 l0 = tr_read<v_rd_off(D0, 0, 0)>(vb), h0 = tr_read<v_rd_off(D0, 0, 1)>(vb), l1 = tr_read<v_rd_off(D0, 1, 0)>(vb), h1 = tr_read<v_rd_off(D0, 1, 1)>(vb);
;   const s16x4 l2 = tr_read<v_rd_off(D0, 2, 0)>(vb), h2 = tr_read<v_rd_off(D0, 2, 1)>(vb), l3 = tr_read<v_rd_off(D0, 3, 0)>(vb), h3 = tr_read<v_rd_off(D0, 3, 1)>(vb);
;   asm volatile("s_waitcnt lgkmcnt(0)" ::: "memory"); SBAR();
;     ...
;   od = __builtin_amdgcn_mfma_f32_32x32x16_bf16(pa0, PK(l0, h0), od, 0, 0, 0);
;   od = __builtin_amdgcn_mfma_f32_32x32x16_bf16(pa1, PK(l1, h1), od, 0, 0, 0);
;   od = __builtin_amdgcn_mfma_f32_32x32x16_bf16(pa2, PK(l2, h2), od, 0, 0, 0);
;   od = __builtin_amdgcn_mfma_f32_32x32x16_bf16(pa3, PK(l3, h3), od, 0, 0, 0);
;     ...
; }
; __device__ __forceinline__ void pv_d0(f32x16* o, int vb, bf16x8 pa0, bf16x8 pa1, bf16x8 pa2, bf16x8 pa3) {
;   pv_one<0>(o[0], vb, pa0, pa1, pa2, pa3); pv_one<1>(o[1], vb, pa0, pa1, pa2, pa3); pv_one<2>(o[2], vb, pa0, pa1, pa2, pa3); pv_one<3>(o[3], vb, pa0, pa1, pa2, pa3);
; template <typename TQ>
; __device__ __forceinline__ void attn_dense_body(const TQ* __restrict__ Qb, const bf16* __restrict__ Kh, const bf16* __restrict__ Vh,
;                                                 unsigned short* __restrict__ Ob, int seq, char* lds, const int wave_s) {
;     ...
;     SLOAD(SO, (j + SDEPTH) * KVBLK); SBAR();
;     pv_d0(o, vb0, pa0, pa1, pa2, pa3); partialSM(pB0, pB1, m_reg, mnB, alB);
	v_mfma_f32_32x32x16_bf16 v[64:79], v[214:217], v[96:99], v[64:79]
	v_cvt_pk_bf16_f32 v171, v154, v155
	s_add_u32 s40, s52, 0x18000
	s_addc_u32 s41, s53, 0
	global_load_dwordx4 v[156:159], v176, s[40:41]
	v_cvt_pk_bf16_f32 v169, v148, v149
	global_load_dwordx4 v[152:155], v176, s[40:41] offset:-512
	v_cvt_pk_bf16_f32 v172, v150, v151
	global_load_dwordx4 v[148:151], v176, s[52:53] offset:-512
	v_cvt_pk_bf16_f32 v170, v146, v147
	v_cvt_pk_bf16_f32 v173, v144, v145
	global_load_dwordx4 v[144:147], v176, s[52:53]
	s_add_u32 s52, s52, 0x30000
	s_addc_u32 s53, s53, 0
	ds_read_b64_tr_b16 v[210:211], v184 offset:0
	ds_read_b64_tr_b16 v[212:213], v184 offset:0x800
	ds_read_b64_tr_b16 v[214:215], v184 offset:0x1000
	ds_read_b64_tr_b16 v[216:217], v184 offset:0x1800
	ds_read_b64_tr_b16 v[224:225], v184 offset:0x2000
	ds_read_b64_tr_b16 v[226:227], v184 offset:0x2800
	ds_read_b64_tr_b16 v[228:229], v184 offset:0x3000
	ds_read_b64_tr_b16 v[230:231], v184 offset:0x3800
	s_waitcnt lgkmcnt(0)
	v_mfma_f32_32x32x16_bf16 v[0:15], v[160:163], v[210:213], v[0:15]
	ds_read_b64_tr_b16 v[210:211], v184 offset:0x200
	ds_read_b64_tr_b16 v[212:213], v184 offset:0xa00
	v_mfma_f32_32x32x16_bf16 v[0:15], v[206:209], v[214:217], v[0:15]
	ds_read_b64_tr_b16 v[214:215], v184 offset:0x1200
	ds_read_b64_tr_b16 v[216:217], v184 offset:0x1a00
	v_mfma_f32_32x32x16_bf16 v[0:15], v[166:169], v[224:227], v[0:15]
	ds_read_b64_tr_b16 v[224:225], v184 offset:0x2200
	ds_read_b64_tr_b16 v[226:227], v184 offset:0x2a00
	v_mfma_f32_32x32x16_bf16 v[0:15], v[170:173], v[228:231], v[0:15]
	ds_read_b64_tr_b16 v[228:229], v184 offset:0x3200
	ds_read_b64_tr_b16 v[230:231], v184 offset:0x3a00
	s_waitcnt lgkmcnt(0)
	v_mfma_f32_32x32x16_bf16 v[48:63], v[160:163], v[210:213], v[48:63]
	ds_read_b64_tr_b16 v[210:211], v184 offset:0x400
	ds_read_b64_tr_b16 v[212:213], v184 offset:0xc00
	v_mfma_f32_32x32x16_bf16 v[48:63], v[206:209], v[214:217], v[48:63]
	ds_read_b64_tr_b16 v[214:215], v184 offset:0x1400
	ds_read_b64_tr_b16 v[216:217], v184 offset:0x1c00
	v_mfma_f32_32x32x16_bf16 v[48:63], v[166:169], v[224:227], v[48:63]
	ds_read_b64_tr_b16 v[224:225], v184 offset:0x2400
	ds_read_b64_tr_b16 v[226:227], v184 offset:0x2c00
	v_mfma_f32_32x32x16_bf16 v[48:63], v[170:173], v[228:231], v[48:63]
	ds_read_b64_tr_b16 v[228:229], v184 offset:0x3400
	ds_read_b64_tr_b16 v[230:231], v184 offset:0x3c00
	s_waitcnt lgkmcnt(0)
	v_mfma_f32_32x32x16_bf16 v[32:47], v[160:163], v[210:213], v[32:47]
	ds_read_b64_tr_b16 v[210:211], v184 offset:0x600
	ds_read_b64_tr_b16 v[212:213], v184 offset:0xe00
	v_mfma_f32_32x32x16_bf16 v[32:47], v[206:209], v[214:217], v[32:47]
	ds_read_b64_tr_b16 v[214:215], v184 offset:0x1600
	ds_read_b64_tr_b16 v[216:217], v184 offset:0x1e00
	v_mfma_f32_32x32x16_bf16 v[32:47], v[166:169], v[224:227], v[32:47]
	ds_read_b64_tr_b16 v[224:225], v184 offset:0x2600
	ds_read_b64_tr_b16 v[226:227], v184 offset:0x2e00
	v_mfma_f32_32x32x16_bf16 v[32:47], v[170:173], v[228:231], v[32:47]
	ds_read_b64_tr_b16 v[228:229], v184 offset:0x3600
	ds_read_b64_tr_b16 v[230:231], v184 offset:0x3e00
	s_waitcnt lgkmcnt(0)
	v_mfma_f32_32x32x16_bf16 v[16:31], v[160:163], v[210:213], v[16:31]
	v_max_f32_e32 v160, v80, v81
	v_max3_f32 v160, v160, v82, v83
	v_max3_f32 v160, v160, v84, v85
	v_max3_f32 v160, v160, v86, v87
	v_max3_f32 v160, v160, v88, v89
	v_max3_f32 v160, v160, v90, v91
	v_max3_f32 v160, v160, v92, v93
	v_mfma_f32_32x32x16_bf16 v[16:31], v[206:209], v[214:217], v[16:31]
	v_max3_f32 v160, v160, v94, v95
	v_max3_f32 v160, v160, v64, v65
	v_max3_f32 v160, v160, v66, v67
	v_max3_f32 v160, v160, v68, v69
	v_max3_f32 v160, v160, v70, v71
	v_max3_f32 v160, v160, v72, v73
	v_max3_f32 v160, v160, v74, v75
	v_max3_f32 v160, v160, v76, v77
	v_mfma_f32_32x32x16_bf16 v[16:31], v[166:169], v[224:227], v[16:31]
	v_max3_f32 v160, v160, v78, v79
	v_mov_b32_e32 v161, v160
	s_nop 1
	v_permlane32_swap_b32_e32 v160, v161
	v_max_f32_e32 v160, v160, v161
	v_sub_f32_e32 v161, v160, v164
	v_cmp_ge_f32_e32 vcc, s9, v161
	v_mfma_f32_32x32x16_bf16 v[16:31], v[170:173], v[228:231], v[16:31]
	s_cmp_eq_u64 vcc, exec
	s_cbranch_scc0 .Lattn_slow_a
	v_mov_b32_e32 v205, 1.0
	v_mov_b32_e32 v206, v164
	s_waitcnt vmcnt(4)
	ds_write_b128 v187, v[128:131]
	ds_write_b128 v187, v[136:139] offset:8192
	ds_write_b128 v185, v[132:135] offset:32768
	ds_write_b128 v185, v[140:143] offset:40960
